# dual-tile shared-A mainloop (hand-written) in phases 1 and 9: 25% fewer L2->LDS loads
# speedup vs baseline: 1.0180x; 1.0180x over previous
_Z8fwd_mega6Paramsii:
	s_mov_b32 s95, 0
	s_load_dwordx2 s[52:53], s[0:1], 0x130
	s_add_u32 s6, s0, 0x130
	v_and_b32_e32 v168, 0x3ff, v0
	s_addc_u32 s7, s1, 0
	v_cmp_eq_u32_e64 s[4:5], 0, v168
	s_and_saveexec_b64 s[8:9], s[4:5]
	v_mov_b32_e32 v2, 0
	v_mov_b32_e32 v3, v2
	v_mov_b32_e32 v4, v2
	v_mov_b32_e32 v5, v2
	ds_write_b128 v2, v[2:5]
	s_or_b64 exec, exec, s[8:9]
	s_load_dword s78, s[0:1], 0x138
	s_load_dwordx2 s[46:47], s[0:1], 0x120
	s_waitcnt lgkmcnt(0)
	s_barrier
	s_getreg_b32 s3, hwreg(HW_REG_XCC_ID, 0, 4)
	s_and_b32 s33, s3, 15
	s_and_saveexec_b64 s[8:9], s[4:5]
	s_cbranch_execz .LBB0_5
	s_mov_b64 s[10:11], exec
	v_mbcnt_lo_u32_b32 v1, s10, 0
	v_mbcnt_hi_u32_b32 v1, s11, v1
	v_cmp_eq_u32_e32 vcc, 0, v1
	s_and_b64 s[12:13], exec, vcc
	s_mov_b64 exec, s[12:13]
	s_cbranch_execz .LBB0_5
	s_lshl_b32 s3, s33, 8
	s_bcnt1_i32_b64 s10, s[10:11]
	v_mov_b32_e32 v1, s3
	v_mov_b32_e32 v2, s10
	global_atomic_add v1, v2, s[46:47] offset:1024

.LBB0_104:
	s_cmp_eq_u32 s95, 2
	s_cbranch_scc1 .Lgp1_unpark
	v_lshrrev_b32_e32 v78, 3, v168
	v_lshrrev_b32_e32 v79, 4, v168
	v_xor_b32_e32 v79, v79, v168
	v_and_b32_e32 v79, 7, v79
	v_lshlrev_b32_e32 v79, 4, v79
	v_lshl_or_b32 v64, v78, 11, v79
	v_add_u32_e32 v66, 0x10000, v64
	v_add_u32_e32 v67, 0x20000, v64
	v_add_u32_e32 v77, 0x30000, v64
	s_load_dwordx2 s[90:91], s[0:1], 0xa0
	s_load_dwordx2 s[92:93], s[0:1], 0xa8
	v_lshrrev_b32_e32 v79, 6, v168
	s_nop 1
	v_readfirstlane_b32 s97, v79
	s_nop 3
	s_lshl_b32 s96, s97, 10
	s_add_u32 s96, s96, 16
	s_add_u32 s94, s66, s67
	s_cmp_lt_i32 s94, s68
	s_cselect_b32 s95, 1, 0
	s_cmp_lg_u64 s[8:9], 0
	s_cselect_b32 s95, 0, s95
	s_cmp_ge_u32 s94, 0x180
	s_cselect_b32 s97, 1, 0
	s_mul_i32 s100, s97, 0x180
	s_sub_u32 s100, s94, s100
	s_lshr_b32 s101, s100, 3
	s_and_b32 s100, s100, 7
	s_lshl_b32 s97, s97, 3
	s_add_u32 s100, s100, s97
	s_add_u32 s100, s100, s3
	s_cmp_lg_u32 s100, s60
	s_cselect_b32 s95, 0, s95
	s_cmp_eq_u32 s95, 1
	s_cselect_b32 s101, s101, s58
	s_waitcnt lgkmcnt(0)
	s_lshl_b32 s101, s101, 18
	s_add_u32 s98, s92, s101
	s_addc_u32 s99, s93, 0
	s_lshl_b32 s94, s58, 18
	s_add_u32 s92, s92, s94
	s_addc_u32 s93, s93, 0
	s_lshl_b32 s94, s60, 18
	s_add_u32 s90, s90, s94
	s_addc_u32 s91, s91, 0
	s_barrier
	s_add_u32 m0, s96, 0x0
	s_nop 0
	global_load_lds_dwordx4 v64, s[90:91]
	s_add_u32 m0, s96, 0x1000
	s_nop 0
	global_load_lds_dwordx4 v66, s[90:91]
	s_add_u32 m0, s96, 0x2000
	s_nop 0
	global_load_lds_dwordx4 v67, s[90:91]
	s_add_u32 m0, s96, 0x3000
	s_nop 0
	global_load_lds_dwordx4 v77, s[90:91]
	s_add_u32 m0, s96, 0x4000
	s_nop 0
	global_load_lds_dwordx4 v64, s[92:93]
	s_add_u32 m0, s96, 0x5000
	s_nop 0
	global_load_lds_dwordx4 v66, s[92:93]
	s_add_u32 m0, s96, 0x6000
	s_nop 0
	global_load_lds_dwordx4 v67, s[92:93]
	s_add_u32 m0, s96, 0x7000
	s_nop 0
	global_load_lds_dwordx4 v77, s[92:93]
	s_add_u32 m0, s96, 0x8000
	s_nop 0
	global_load_lds_dwordx4 v64, s[98:99]
	s_add_u32 m0, s96, 0x9000
	s_nop 0
	global_load_lds_dwordx4 v66, s[98:99]
	s_add_u32 m0, s96, 0xa000
	s_nop 0
	global_load_lds_dwordx4 v67, s[98:99]
	s_add_u32 m0, s96, 0xb000
	s_nop 0
	global_load_lds_dwordx4 v77, s[98:99]
	s_add_u32 s90, s90, 0x80
	s_addc_u32 s91, s91, 0
	s_add_u32 s92, s92, 0x80
	s_addc_u32 s93, s93, 0
	s_add_u32 s98, s98, 0x80
	s_addc_u32 s99, s99, 0
	s_and_b64 vcc, exec, s[6:7]
	s_cbranch_vccnz .Lgp1_nosleep
	s_sleep 8
.Lgp1_nosleep:
	v_mov_b32_e32 v56, 0
	v_mov_b32_e32 v57, v56
	v_mov_b32_e32 v58, v56
	v_mov_b32_e32 v59, v56
	v_mov_b32_e32 v48, v56
	v_mov_b32_e32 v49, v56
	v_mov_b32_e32 v50, v56
	v_mov_b32_e32 v51, v56
	v_mov_b32_e32 v60, v56
	v_mov_b32_e32 v61, v56
	v_mov_b32_e32 v62, v56
	v_mov_b32_e32 v63, v56
	v_mov_b32_e32 v52, v56
	v_mov_b32_e32 v53, v56
	v_mov_b32_e32 v54, v56
	v_mov_b32_e32 v55, v56
	v_mov_b32_e32 v40, v56
	v_mov_b32_e32 v41, v56
	v_mov_b32_e32 v42, v56
	v_mov_b32_e32 v43, v56
	v_mov_b32_e32 v32, v56
	v_mov_b32_e32 v33, v56
	v_mov_b32_e32 v34, v56
	v_mov_b32_e32 v35, v56
	v_mov_b32_e32 v44, v56
	v_mov_b32_e32 v45, v56
	v_mov_b32_e32 v46, v56
	v_mov_b32_e32 v47, v56
	v_mov_b32_e32 v36, v56
	v_mov_b32_e32 v37, v56
	v_mov_b32_e32 v38, v56
	v_mov_b32_e32 v39, v56
	v_mov_b32_e32 v24, v56
	v_mov_b32_e32 v25, v56
	v_mov_b32_e32 v26, v56
	v_mov_b32_e32 v27, v56
	v_mov_b32_e32 v16, v56
	v_mov_b32_e32 v17, v56
	v_mov_b32_e32 v18, v56
	v_mov_b32_e32 v19, v56
	v_mov_b32_e32 v28, v56
	v_mov_b32_e32 v29, v56
	v_mov_b32_e32 v30, v56
	v_mov_b32_e32 v31, v56
	v_mov_b32_e32 v20, v56
	v_mov_b32_e32 v21, v56
	v_mov_b32_e32 v22, v56
	v_mov_b32_e32 v23, v56
	v_mov_b32_e32 v8, v56
	v_mov_b32_e32 v9, v56
	v_mov_b32_e32 v10, v56
	v_mov_b32_e32 v11, v56
	v_mov_b32_e32 v0, v56
	v_mov_b32_e32 v1, v56
	v_mov_b32_e32 v2, v56
	v_mov_b32_e32 v3, v56
	v_mov_b32_e32 v12, v56
	v_mov_b32_e32 v13, v56
	v_mov_b32_e32 v14, v56
	v_mov_b32_e32 v15, v56
	v_mov_b32_e32 v4, v56
	v_mov_b32_e32 v5, v56
	v_mov_b32_e32 v6, v56
	v_mov_b32_e32 v7, v56
	v_mov_b32_e32 v116, v56
	v_mov_b32_e32 v117, v56
	v_mov_b32_e32 v118, v56
	v_mov_b32_e32 v119, v56
	v_mov_b32_e32 v120, v56
	v_mov_b32_e32 v121, v56
	v_mov_b32_e32 v122, v56
	v_mov_b32_e32 v123, v56
	v_mov_b32_e32 v124, v56
	v_mov_b32_e32 v125, v56
	v_mov_b32_e32 v126, v56
	v_mov_b32_e32 v127, v56
	v_mov_b32_e32 v128, v56
	v_mov_b32_e32 v129, v56
	v_mov_b32_e32 v130, v56
	v_mov_b32_e32 v131, v56
	v_mov_b32_e32 v132, v56
	v_mov_b32_e32 v133, v56
	v_mov_b32_e32 v134, v56
	v_mov_b32_e32 v135, v56
	v_mov_b32_e32 v136, v56
	v_mov_b32_e32 v137, v56
	v_mov_b32_e32 v138, v56
	v_mov_b32_e32 v139, v56
	v_mov_b32_e32 v140, v56
	v_mov_b32_e32 v141, v56
	v_mov_b32_e32 v142, v56
	v_mov_b32_e32 v143, v56
	v_mov_b32_e32 v144, v56
	v_mov_b32_e32 v145, v56
	v_mov_b32_e32 v146, v56
	v_mov_b32_e32 v147, v56
	v_mov_b32_e32 v148, v56
	v_mov_b32_e32 v149, v56
	v_mov_b32_e32 v150, v56
	v_mov_b32_e32 v151, v56
	v_mov_b32_e32 v152, v56
	v_mov_b32_e32 v153, v56
	v_mov_b32_e32 v154, v56
	v_mov_b32_e32 v155, v56
	v_mov_b32_e32 v156, v56
	v_mov_b32_e32 v157, v56
	v_mov_b32_e32 v158, v56
	v_mov_b32_e32 v159, v56
	v_mov_b32_e32 v160, v56
	v_mov_b32_e32 v161, v56
	v_mov_b32_e32 v162, v56
	v_mov_b32_e32 v163, v56
	v_mov_b32_e32 v164, v56
	v_mov_b32_e32 v165, v56
	v_mov_b32_e32 v166, v56
	v_mov_b32_e32 v167, v56
	v_mov_b32_e32 v172, v56
	v_mov_b32_e32 v173, v56
	v_mov_b32_e32 v174, v56
	v_mov_b32_e32 v175, v56
	v_mov_b32_e32 v176, v56
	v_mov_b32_e32 v177, v56
	v_mov_b32_e32 v178, v56
	v_mov_b32_e32 v179, v56
	v_mov_b32_e32 v180, v56
	v_mov_b32_e32 v181, v56
	v_mov_b32_e32 v182, v56
	v_mov_b32_e32 v183, v56
	s_mov_b32 s94, 0
.Lgp1_loop:
	s_waitcnt vmcnt(0) lgkmcnt(0)
	s_barrier
	ds_read_b128 v[184:187], v86
	ds_read_b128 v[188:191], v86 offset:2048
	ds_read_b128 v[192:195], v86 offset:4096
	ds_read_b128 v[196:199], v86 offset:6144
	ds_read_b128 v[216:219], v87 offset:16384
	ds_read_b128 v[220:223], v87 offset:18432
	ds_read_b128 v[224:227], v87 offset:20480
	ds_read_b128 v[228:231], v87 offset:22528
	ds_read_b128 v[248:251], v87 offset:32768
	ds_read_b128 v[252:255], v87 offset:34816
	ds_read_b128 v[68:71], v87 offset:36864
	ds_read_b128 v[72:75], v87 offset:38912
	ds_read_b128 v[200:203], v88
	ds_read_b128 v[204:207], v88 offset:2048
	ds_read_b128 v[208:211], v88 offset:4096
	ds_read_b128 v[212:215], v88 offset:6144
	ds_read_b128 v[232:235], v89 offset:16384
	ds_read_b128 v[236:239], v89 offset:18432
	ds_read_b128 v[240:243], v89 offset:20480
	ds_read_b128 v[244:247], v89 offset:22528
	ds_read_b128 v[96:99], v89 offset:32768
	ds_read_b128 v[100:103], v89 offset:34816
	ds_read_b128 v[104:107], v89 offset:36864
	ds_read_b128 v[112:115], v89 offset:38912
	s_waitcnt lgkmcnt(0)
	s_barrier
	s_cmp_eq_u32 s94, 15
	s_cbranch_scc1 .Lgp1_last
	s_add_u32 m0, s96, 0x0
	v_mfma_f32_16x16x32_bf16 v[56:59], v[216:219], v[184:187], v[56:59]
	global_load_lds_dwordx4 v64, s[90:91]
	v_mfma_f32_16x16x32_bf16 v[116:119], v[248:251], v[184:187], v[116:119]
	s_add_u32 m0, s96, 0x1000
	v_mfma_f32_16x16x32_bf16 v[48:51], v[220:223], v[184:187], v[48:51]
	global_load_lds_dwordx4 v66, s[90:91]
	v_mfma_f32_16x16x32_bf16 v[120:123], v[252:255], v[184:187], v[120:123]
	s_add_u32 m0, s96, 0x2000
	v_mfma_f32_16x16x32_bf16 v[60:63], v[224:227], v[184:187], v[60:63]
	global_load_lds_dwordx4 v67, s[90:91]
	v_mfma_f32_16x16x32_bf16 v[124:127], v[68:71], v[184:187], v[124:127]
	s_add_u32 m0, s96, 0x3000
	v_mfma_f32_16x16x32_bf16 v[52:55], v[228:231], v[184:187], v[52:55]
	global_load_lds_dwordx4 v77, s[90:91]
	v_mfma_f32_16x16x32_bf16 v[128:131], v[72:75], v[184:187], v[128:131]
	s_add_u32 m0, s96, 0x4000
	v_mfma_f32_16x16x32_bf16 v[40:43], v[216:219], v[188:191], v[40:43]
	global_load_lds_dwordx4 v64, s[92:93]
	v_mfma_f32_16x16x32_bf16 v[132:135], v[248:251], v[188:191], v[132:135]
	s_add_u32 m0, s96, 0x5000
	v_mfma_f32_16x16x32_bf16 v[32:35], v[220:223], v[188:191], v[32:35]
	global_load_lds_dwordx4 v66, s[92:93]
	v_mfma_f32_16x16x32_bf16 v[136:139], v[252:255], v[188:191], v[136:139]
	s_add_u32 m0, s96, 0x6000
	v_mfma_f32_16x16x32_bf16 v[44:47], v[224:227], v[188:191], v[44:47]
	global_load_lds_dwordx4 v67, s[92:93]
	v_mfma_f32_16x16x32_bf16 v[140:143], v[68:71], v[188:191], v[140:143]
	s_add_u32 m0, s96, 0x7000
	v_mfma_f32_16x16x32_bf16 v[36:39], v[228:231], v[188:191], v[36:39]
	global_load_lds_dwordx4 v77, s[92:93]
	v_mfma_f32_16x16x32_bf16 v[144:147], v[72:75], v[188:191], v[144:147]
	s_add_u32 m0, s96, 0x8000
	v_mfma_f32_16x16x32_bf16 v[24:27], v[216:219], v[192:195], v[24:27]
	global_load_lds_dwordx4 v64, s[98:99]
	v_mfma_f32_16x16x32_bf16 v[148:151], v[248:251], v[192:195], v[148:151]
	s_add_u32 m0, s96, 0x9000
	v_mfma_f32_16x16x32_bf16 v[16:19], v[220:223], v[192:195], v[16:19]
	global_load_lds_dwordx4 v66, s[98:99]
	v_mfma_f32_16x16x32_bf16 v[152:155], v[252:255], v[192:195], v[152:155]
	s_add_u32 m0, s96, 0xa000
	v_mfma_f32_16x16x32_bf16 v[28:31], v[224:227], v[192:195], v[28:31]
	global_load_lds_dwordx4 v67, s[98:99]
	v_mfma_f32_16x16x32_bf16 v[156:159], v[68:71], v[192:195], v[156:159]
	s_add_u32 m0, s96, 0xb000
	v_mfma_f32_16x16x32_bf16 v[20:23], v[228:231], v[192:195], v[20:23]
	global_load_lds_dwordx4 v77, s[98:99]
	s_add_u32 s90, s90, 0x80
	s_addc_u32 s91, s91, 0
	s_add_u32 s92, s92, 0x80
	s_addc_u32 s93, s93, 0
	s_add_u32 s98, s98, 0x80
	s_addc_u32 s99, s99, 0
	v_mfma_f32_16x16x32_bf16 v[160:163], v[72:75], v[192:195], v[160:163]
	v_mfma_f32_16x16x32_bf16 v[8:11], v[216:219], v[196:199], v[8:11]
	v_mfma_f32_16x16x32_bf16 v[164:167], v[248:251], v[196:199], v[164:167]
	v_mfma_f32_16x16x32_bf16 v[0:3], v[220:223], v[196:199], v[0:3]
	v_mfma_f32_16x16x32_bf16 v[172:175], v[252:255], v[196:199], v[172:175]
	v_mfma_f32_16x16x32_bf16 v[12:15], v[224:227], v[196:199], v[12:15]
	v_mfma_f32_16x16x32_bf16 v[176:179], v[68:71], v[196:199], v[176:179]
	v_mfma_f32_16x16x32_bf16 v[4:7], v[228:231], v[196:199], v[4:7]
	v_mfma_f32_16x16x32_bf16 v[180:183], v[72:75], v[196:199], v[180:183]
	v_mfma_f32_16x16x32_bf16 v[56:59], v[232:235], v[200:203], v[56:59]
	v_mfma_f32_16x16x32_bf16 v[116:119], v[96:99], v[200:203], v[116:119]
	v_mfma_f32_16x16x32_bf16 v[48:51], v[236:239], v[200:203], v[48:51]
	v_mfma_f32_16x16x32_bf16 v[120:123], v[100:103], v[200:203], v[120:123]
	v_mfma_f32_16x16x32_bf16 v[60:63], v[240:243], v[200:203], v[60:63]
	v_mfma_f32_16x16x32_bf16 v[124:127], v[104:107], v[200:203], v[124:127]
	v_mfma_f32_16x16x32_bf16 v[52:55], v[244:247], v[200:203], v[52:55]
	v_mfma_f32_16x16x32_bf16 v[128:131], v[112:115], v[200:203], v[128:131]
	v_mfma_f32_16x16x32_bf16 v[40:43], v[232:235], v[204:207], v[40:43]
	v_mfma_f32_16x16x32_bf16 v[132:135], v[96:99], v[204:207], v[132:135]
	v_mfma_f32_16x16x32_bf16 v[32:35], v[236:239], v[204:207], v[32:35]
	v_mfma_f32_16x16x32_bf16 v[136:139], v[100:103], v[204:207], v[136:139]
	v_mfma_f32_16x16x32_bf16 v[44:47], v[240:243], v[204:207], v[44:47]
	v_mfma_f32_16x16x32_bf16 v[140:143], v[104:107], v[204:207], v[140:143]
	v_mfma_f32_16x16x32_bf16 v[36:39], v[244:247], v[204:207], v[36:39]
	v_mfma_f32_16x16x32_bf16 v[144:147], v[112:115], v[204:207], v[144:147]
	v_mfma_f32_16x16x32_bf16 v[24:27], v[232:235], v[208:211], v[24:27]
	v_mfma_f32_16x16x32_bf16 v[148:151], v[96:99], v[208:211], v[148:151]
	v_mfma_f32_16x16x32_bf16 v[16:19], v[236:239], v[208:211], v[16:19]
	v_mfma_f32_16x16x32_bf16 v[152:155], v[100:103], v[208:211], v[152:155]
	v_mfma_f32_16x16x32_bf16 v[28:31], v[240:243], v[208:211], v[28:31]
	v_mfma_f32_16x16x32_bf16 v[156:159], v[104:107], v[208:211], v[156:159]
	v_mfma_f32_16x16x32_bf16 v[20:23], v[244:247], v[208:211], v[20:23]
	v_mfma_f32_16x16x32_bf16 v[160:163], v[112:115], v[208:211], v[160:163]
	v_mfma_f32_16x16x32_bf16 v[8:11], v[232:235], v[212:215], v[8:11]
	v_mfma_f32_16x16x32_bf16 v[164:167], v[96:99], v[212:215], v[164:167]
	v_mfma_f32_16x16x32_bf16 v[0:3], v[236:239], v[212:215], v[0:3]
	v_mfma_f32_16x16x32_bf16 v[172:175], v[100:103], v[212:215], v[172:175]
	v_mfma_f32_16x16x32_bf16 v[12:15], v[240:243], v[212:215], v[12:15]
	v_mfma_f32_16x16x32_bf16 v[176:179], v[104:107], v[212:215], v[176:179]
	v_mfma_f32_16x16x32_bf16 v[4:7], v[244:247], v[212:215], v[4:7]
	v_mfma_f32_16x16x32_bf16 v[180:183], v[112:115], v[212:215], v[180:183]
	s_add_u32 s94, s94, 1
	s_branch .Lgp1_loop
.Lgp1_last:
	v_mfma_f32_16x16x32_bf16 v[56:59], v[216:219], v[184:187], v[56:59]
	v_mfma_f32_16x16x32_bf16 v[116:119], v[248:251], v[184:187], v[116:119]
	v_mfma_f32_16x16x32_bf16 v[48:51], v[220:223], v[184:187], v[48:51]
	v_mfma_f32_16x16x32_bf16 v[120:123], v[252:255], v[184:187], v[120:123]
	v_mfma_f32_16x16x32_bf16 v[60:63], v[224:227], v[184:187], v[60:63]
	v_mfma_f32_16x16x32_bf16 v[124:127], v[68:71], v[184:187], v[124:127]
	v_mfma_f32_16x16x32_bf16 v[52:55], v[228:231], v[184:187], v[52:55]
	v_mfma_f32_16x16x32_bf16 v[128:131], v[72:75], v[184:187], v[128:131]
	v_mfma_f32_16x16x32_bf16 v[40:43], v[216:219], v[188:191], v[40:43]
	v_mfma_f32_16x16x32_bf16 v[132:135], v[248:251], v[188:191], v[132:135]
	v_mfma_f32_16x16x32_bf16 v[32:35], v[220:223], v[188:191], v[32:35]
	v_mfma_f32_16x16x32_bf16 v[136:139], v[252:255], v[188:191], v[136:139]
	v_mfma_f32_16x16x32_bf16 v[44:47], v[224:227], v[188:191], v[44:47]
	v_mfma_f32_16x16x32_bf16 v[140:143], v[68:71], v[188:191], v[140:143]
	v_mfma_f32_16x16x32_bf16 v[36:39], v[228:231], v[188:191], v[36:39]
	v_mfma_f32_16x16x32_bf16 v[144:147], v[72:75], v[188:191], v[144:147]
	v_mfma_f32_16x16x32_bf16 v[24:27], v[216:219], v[192:195], v[24:27]
	v_mfma_f32_16x16x32_bf16 v[148:151], v[248:251], v[192:195], v[148:151]
	v_mfma_f32_16x16x32_bf16 v[16:19], v[220:223], v[192:195], v[16:19]
	v_mfma_f32_16x16x32_bf16 v[152:155], v[252:255], v[192:195], v[152:155]
	v_mfma_f32_16x16x32_bf16 v[28:31], v[224:227], v[192:195], v[28:31]
	v_mfma_f32_16x16x32_bf16 v[156:159], v[68:71], v[192:195], v[156:159]
	v_mfma_f32_16x16x32_bf16 v[20:23], v[228:231], v[192:195], v[20:23]
	v_mfma_f32_16x16x32_bf16 v[160:163], v[72:75], v[192:195], v[160:163]
	v_mfma_f32_16x16x32_bf16 v[8:11], v[216:219], v[196:199], v[8:11]
	v_mfma_f32_16x16x32_bf16 v[164:167], v[248:251], v[196:199], v[164:167]
	v_mfma_f32_16x16x32_bf16 v[0:3], v[220:223], v[196:199], v[0:3]
	v_mfma_f32_16x16x32_bf16 v[172:175], v[252:255], v[196:199], v[172:175]
	v_mfma_f32_16x16x32_bf16 v[12:15], v[224:227], v[196:199], v[12:15]
	v_mfma_f32_16x16x32_bf16 v[176:179], v[68:71], v[196:199], v[176:179]
	v_mfma_f32_16x16x32_bf16 v[4:7], v[228:231], v[196:199], v[4:7]
	v_mfma_f32_16x16x32_bf16 v[180:183], v[72:75], v[196:199], v[180:183]
	v_mfma_f32_16x16x32_bf16 v[56:59], v[232:235], v[200:203], v[56:59]
	v_mfma_f32_16x16x32_bf16 v[116:119], v[96:99], v[200:203], v[116:119]
	v_mfma_f32_16x16x32_bf16 v[48:51], v[236:239], v[200:203], v[48:51]
	v_mfma_f32_16x16x32_bf16 v[120:123], v[100:103], v[200:203], v[120:123]
	v_mfma_f32_16x16x32_bf16 v[60:63], v[240:243], v[200:203], v[60:63]
	v_mfma_f32_16x16x32_bf16 v[124:127], v[104:107], v[200:203], v[124:127]
	v_mfma_f32_16x16x32_bf16 v[52:55], v[244:247], v[200:203], v[52:55]
	v_mfma_f32_16x16x32_bf16 v[128:131], v[112:115], v[200:203], v[128:131]
	v_mfma_f32_16x16x32_bf16 v[40:43], v[232:235], v[204:207], v[40:43]
	v_mfma_f32_16x16x32_bf16 v[132:135], v[96:99], v[204:207], v[132:135]
	v_mfma_f32_16x16x32_bf16 v[32:35], v[236:239], v[204:207], v[32:35]
	v_mfma_f32_16x16x32_bf16 v[136:139], v[100:103], v[204:207], v[136:139]
	v_mfma_f32_16x16x32_bf16 v[44:47], v[240:243], v[204:207], v[44:47]
	v_mfma_f32_16x16x32_bf16 v[140:143], v[104:107], v[204:207], v[140:143]
	v_mfma_f32_16x16x32_bf16 v[36:39], v[244:247], v[204:207], v[36:39]
	v_mfma_f32_16x16x32_bf16 v[144:147], v[112:115], v[204:207], v[144:147]
	v_mfma_f32_16x16x32_bf16 v[24:27], v[232:235], v[208:211], v[24:27]
	v_mfma_f32_16x16x32_bf16 v[148:151], v[96:99], v[208:211], v[148:151]
	v_mfma_f32_16x16x32_bf16 v[16:19], v[236:239], v[208:211], v[16:19]
	v_mfma_f32_16x16x32_bf16 v[152:155], v[100:103], v[208:211], v[152:155]
	v_mfma_f32_16x16x32_bf16 v[28:31], v[240:243], v[208:211], v[28:31]
	v_mfma_f32_16x16x32_bf16 v[156:159], v[104:107], v[208:211], v[156:159]
	v_mfma_f32_16x16x32_bf16 v[20:23], v[244:247], v[208:211], v[20:23]
	v_mfma_f32_16x16x32_bf16 v[160:163], v[112:115], v[208:211], v[160:163]
	v_mfma_f32_16x16x32_bf16 v[8:11], v[232:235], v[212:215], v[8:11]
	v_mfma_f32_16x16x32_bf16 v[164:167], v[96:99], v[212:215], v[164:167]
	v_mfma_f32_16x16x32_bf16 v[0:3], v[236:239], v[212:215], v[0:3]
	v_mfma_f32_16x16x32_bf16 v[172:175], v[100:103], v[212:215], v[172:175]
	v_mfma_f32_16x16x32_bf16 v[12:15], v[240:243], v[212:215], v[12:15]
	v_mfma_f32_16x16x32_bf16 v[176:179], v[104:107], v[212:215], v[176:179]
	v_mfma_f32_16x16x32_bf16 v[4:7], v[244:247], v[212:215], v[4:7]
	v_mfma_f32_16x16x32_bf16 v[180:183], v[112:115], v[212:215], v[180:183]
	s_nop 7
	s_nop 3
	s_lshl_b32 s95, s95, 1
	s_branch .Lgp1_done
.Lgp1_unpark:
	v_mov_b32_e32 v56, v116
	v_mov_b32_e32 v57, v117
	v_mov_b32_e32 v58, v118
	v_mov_b32_e32 v59, v119
	v_mov_b32_e32 v48, v120
	v_mov_b32_e32 v49, v121
	v_mov_b32_e32 v50, v122
	v_mov_b32_e32 v51, v123
	v_mov_b32_e32 v60, v124
	v_mov_b32_e32 v61, v125
	v_mov_b32_e32 v62, v126
	v_mov_b32_e32 v63, v127
	v_mov_b32_e32 v52, v128
	v_mov_b32_e32 v53, v129
	v_mov_b32_e32 v54, v130
	v_mov_b32_e32 v55, v131
	v_mov_b32_e32 v40, v132
	v_mov_b32_e32 v41, v133
	v_mov_b32_e32 v42, v134
	v_mov_b32_e32 v43, v135
	v_mov_b32_e32 v32, v136
	v_mov_b32_e32 v33, v137
	v_mov_b32_e32 v34, v138
	v_mov_b32_e32 v35, v139
	v_mov_b32_e32 v44, v140
	v_mov_b32_e32 v45, v141
	v_mov_b32_e32 v46, v142
	v_mov_b32_e32 v47, v143
	v_mov_b32_e32 v36, v144
	v_mov_b32_e32 v37, v145
	v_mov_b32_e32 v38, v146
	v_mov_b32_e32 v39, v147
	v_mov_b32_e32 v24, v148
	v_mov_b32_e32 v25, v149
	v_mov_b32_e32 v26, v150
	v_mov_b32_e32 v27, v151
	v_mov_b32_e32 v16, v152
	v_mov_b32_e32 v17, v153
	v_mov_b32_e32 v18, v154
	v_mov_b32_e32 v19, v155
	v_mov_b32_e32 v28, v156
	v_mov_b32_e32 v29, v157
	v_mov_b32_e32 v30, v158
	v_mov_b32_e32 v31, v159
	v_mov_b32_e32 v20, v160
	v_mov_b32_e32 v21, v161
	v_mov_b32_e32 v22, v162
	v_mov_b32_e32 v23, v163
	v_mov_b32_e32 v8, v164
	v_mov_b32_e32 v9, v165
	v_mov_b32_e32 v10, v166
	v_mov_b32_e32 v11, v167
	v_mov_b32_e32 v0, v172
	v_mov_b32_e32 v1, v173
	v_mov_b32_e32 v2, v174
	v_mov_b32_e32 v3, v175
	v_mov_b32_e32 v12, v176
	v_mov_b32_e32 v13, v177
	v_mov_b32_e32 v14, v178
	v_mov_b32_e32 v15, v179
	v_mov_b32_e32 v4, v180
	v_mov_b32_e32 v5, v181
	v_mov_b32_e32 v6, v182
	v_mov_b32_e32 v7, v183
	s_mov_b32 s95, 0
.Lgp1_done:
	s_cmp_gt_i32 s58, 15
	v_lshl_add_u32 v78, s60, 7, v90
	s_mov_b64 s[60:61], -1
	s_cbranch_scc1 .LBB0_110
	s_and_b64 vcc, exec, s[60:61]
	s_cbranch_vccz .LBB0_99
	s_branch .LBB0_120

.LBB0_664:
	s_cmp_eq_u32 s95, 2
	s_cbranch_scc1 .Lgp9_unpark
	v_lshrrev_b32_e32 v84, 3, v168
	v_lshrrev_b32_e32 v85, 4, v168
	v_xor_b32_e32 v85, v85, v168
	v_and_b32_e32 v85, 7, v85
	v_lshlrev_b32_e32 v85, 4, v85
	v_lshl_or_b32 v72, v84, 11, v85
	v_add_u32_e32 v73, 0x10000, v72
	v_add_u32_e32 v66, 0x20000, v72
	v_add_u32_e32 v67, 0x30000, v72
	s_load_dwordx2 s[90:91], s[0:1], 0xf0
	s_load_dwordx2 s[92:93], s[0:1], 0xc8
	v_lshrrev_b32_e32 v85, 6, v168
	s_nop 1
	v_readfirstlane_b32 s97, v85
	s_nop 3
	s_lshl_b32 s96, s97, 10
	s_add_u32 s96, s96, 16
	s_add_u32 s94, s61, s60
	s_cmp_lt_i32 s94, s62
	s_cselect_b32 s95, 1, 0
	s_cmp_lg_u64 s[12:13], 0
	s_cselect_b32 s95, 0, s95
	s_cmp_ge_u32 s94, 0x80
	s_cselect_b32 s97, 1, 0
	s_mul_i32 s100, s97, 0x80
	s_sub_u32 s100, s94, s100
	s_lshr_b32 s101, s100, 3
	s_and_b32 s100, s100, 7
	s_lshl_b32 s97, s97, 3
	s_add_u32 s100, s100, s97
	s_add_u32 s100, s100, s3
	s_cmp_lg_u32 s100, s50
	s_cselect_b32 s95, 0, s95
	s_cmp_eq_u32 s95, 1
	s_cselect_b32 s101, s101, s48
	s_waitcnt lgkmcnt(0)
	s_lshl_b32 s101, s101, 18
	s_add_u32 s98, s92, s101
	s_addc_u32 s99, s93, 0
	s_lshl_b32 s94, s48, 18
	s_add_u32 s92, s92, s94
	s_addc_u32 s93, s93, 0
	s_lshl_b32 s94, s50, 18
	s_add_u32 s90, s90, s94
	s_addc_u32 s91, s91, 0
	s_waitcnt vmcnt(0)
	s_barrier
	s_add_u32 m0, s96, 0x0
	s_nop 0
	global_load_lds_dwordx4 v72, s[90:91]
	s_add_u32 m0, s96, 0x1000
	s_nop 0
	global_load_lds_dwordx4 v73, s[90:91]
	s_add_u32 m0, s96, 0x2000
	s_nop 0
	global_load_lds_dwordx4 v66, s[90:91]
	s_add_u32 m0, s96, 0x3000
	s_nop 0
	global_load_lds_dwordx4 v67, s[90:91]
	s_add_u32 m0, s96, 0x4000
	s_nop 0
	global_load_lds_dwordx4 v72, s[92:93]
	s_add_u32 m0, s96, 0x5000
	s_nop 0
	global_load_lds_dwordx4 v73, s[92:93]
	s_add_u32 m0, s96, 0x6000
	s_nop 0
	global_load_lds_dwordx4 v66, s[92:93]
	s_add_u32 m0, s96, 0x7000
	s_nop 0
	global_load_lds_dwordx4 v67, s[92:93]
	s_add_u32 m0, s96, 0x8000
	s_nop 0
	global_load_lds_dwordx4 v72, s[98:99]
	s_add_u32 m0, s96, 0x9000
	s_nop 0
	global_load_lds_dwordx4 v73, s[98:99]
	s_add_u32 m0, s96, 0xa000
	s_nop 0
	global_load_lds_dwordx4 v66, s[98:99]
	s_add_u32 m0, s96, 0xb000
	s_nop 0
	global_load_lds_dwordx4 v67, s[98:99]
	s_add_u32 s90, s90, 0x80
	s_addc_u32 s91, s91, 0
	s_add_u32 s92, s92, 0x80
	s_addc_u32 s93, s93, 0
	s_add_u32 s98, s98, 0x80
	s_addc_u32 s99, s99, 0
	s_and_b64 vcc, exec, s[6:7]
	s_cbranch_vccnz .Lgp9_nosleep
	s_sleep 8
.Lgp9_nosleep:
	v_mov_b32_e32 v60, 0
	v_mov_b32_e32 v61, v60
	v_mov_b32_e32 v62, v60
	v_mov_b32_e32 v63, v60
	v_mov_b32_e32 v56, v60
	v_mov_b32_e32 v57, v60
	v_mov_b32_e32 v58, v60
	v_mov_b32_e32 v59, v60
	v_mov_b32_e32 v52, v60
	v_mov_b32_e32 v53, v60
	v_mov_b32_e32 v54, v60
	v_mov_b32_e32 v55, v60
	v_mov_b32_e32 v48, v60
	v_mov_b32_e32 v49, v60
	v_mov_b32_e32 v50, v60
	v_mov_b32_e32 v51, v60
	v_mov_b32_e32 v44, v60
	v_mov_b32_e32 v45, v60
	v_mov_b32_e32 v46, v60
	v_mov_b32_e32 v47, v60
	v_mov_b32_e32 v40, v60
	v_mov_b32_e32 v41, v60
	v_mov_b32_e32 v42, v60
	v_mov_b32_e32 v43, v60
	v_mov_b32_e32 v36, v60
	v_mov_b32_e32 v37, v60
	v_mov_b32_e32 v38, v60
	v_mov_b32_e32 v39, v60
	v_mov_b32_e32 v32, v60
	v_mov_b32_e32 v33, v60
	v_mov_b32_e32 v34, v60
	v_mov_b32_e32 v35, v60
	v_mov_b32_e32 v28, v60
	v_mov_b32_e32 v29, v60
	v_mov_b32_e32 v30, v60
	v_mov_b32_e32 v31, v60
	v_mov_b32_e32 v24, v60
	v_mov_b32_e32 v25, v60
	v_mov_b32_e32 v26, v60
	v_mov_b32_e32 v27, v60
	v_mov_b32_e32 v20, v60
	v_mov_b32_e32 v21, v60
	v_mov_b32_e32 v22, v60
	v_mov_b32_e32 v23, v60
	v_mov_b32_e32 v16, v60
	v_mov_b32_e32 v17, v60
	v_mov_b32_e32 v18, v60
	v_mov_b32_e32 v19, v60
	v_mov_b32_e32 v12, v60
	v_mov_b32_e32 v13, v60
	v_mov_b32_e32 v14, v60
	v_mov_b32_e32 v15, v60
	v_mov_b32_e32 v4, v60
	v_mov_b32_e32 v5, v60
	v_mov_b32_e32 v6, v60
	v_mov_b32_e32 v7, v60
	v_mov_b32_e32 v0, v60
	v_mov_b32_e32 v1, v60
	v_mov_b32_e32 v2, v60
	v_mov_b32_e32 v3, v60
	v_mov_b32_e32 v8, v60
	v_mov_b32_e32 v9, v60
	v_mov_b32_e32 v10, v60
	v_mov_b32_e32 v11, v60
	v_mov_b32_e32 v116, v60
	v_mov_b32_e32 v117, v60
	v_mov_b32_e32 v118, v60
	v_mov_b32_e32 v119, v60
	v_mov_b32_e32 v120, v60
	v_mov_b32_e32 v121, v60
	v_mov_b32_e32 v122, v60
	v_mov_b32_e32 v123, v60
	v_mov_b32_e32 v124, v60
	v_mov_b32_e32 v125, v60
	v_mov_b32_e32 v126, v60
	v_mov_b32_e32 v127, v60
	v_mov_b32_e32 v128, v60
	v_mov_b32_e32 v129, v60
	v_mov_b32_e32 v130, v60
	v_mov_b32_e32 v131, v60
	v_mov_b32_e32 v132, v60
	v_mov_b32_e32 v133, v60
	v_mov_b32_e32 v134, v60
	v_mov_b32_e32 v135, v60
	v_mov_b32_e32 v136, v60
	v_mov_b32_e32 v137, v60
	v_mov_b32_e32 v138, v60
	v_mov_b32_e32 v139, v60
	v_mov_b32_e32 v140, v60
	v_mov_b32_e32 v141, v60
	v_mov_b32_e32 v142, v60
	v_mov_b32_e32 v143, v60
	v_mov_b32_e32 v148, v60
	v_mov_b32_e32 v149, v60
	v_mov_b32_e32 v150, v60
	v_mov_b32_e32 v151, v60
	v_mov_b32_e32 v152, v60
	v_mov_b32_e32 v153, v60
	v_mov_b32_e32 v154, v60
	v_mov_b32_e32 v155, v60
	v_mov_b32_e32 v156, v60
	v_mov_b32_e32 v157, v60
	v_mov_b32_e32 v158, v60
	v_mov_b32_e32 v159, v60
	v_mov_b32_e32 v160, v60
	v_mov_b32_e32 v161, v60
	v_mov_b32_e32 v162, v60
	v_mov_b32_e32 v163, v60
	v_mov_b32_e32 v172, v60
	v_mov_b32_e32 v173, v60
	v_mov_b32_e32 v174, v60
	v_mov_b32_e32 v175, v60
	v_mov_b32_e32 v176, v60
	v_mov_b32_e32 v177, v60
	v_mov_b32_e32 v178, v60
	v_mov_b32_e32 v179, v60
	v_mov_b32_e32 v180, v60
	v_mov_b32_e32 v181, v60
	v_mov_b32_e32 v182, v60
	v_mov_b32_e32 v183, v60
	v_mov_b32_e32 v184, v60
	v_mov_b32_e32 v185, v60
	v_mov_b32_e32 v186, v60
	v_mov_b32_e32 v187, v60
	v_mov_b32_e32 v188, v60
	v_mov_b32_e32 v189, v60
	v_mov_b32_e32 v190, v60
	v_mov_b32_e32 v191, v60
	s_mov_b32 s94, 0
.Lgp9_loop:
	s_waitcnt vmcnt(0) lgkmcnt(0)
	s_barrier
	ds_read_b128 v[192:195], v86
	ds_read_b128 v[204:207], v86 offset:2048
	ds_read_b128 v[208:211], v86 offset:4096
	ds_read_b128 v[212:215], v86 offset:6144
	ds_read_b128 v[232:235], v87 offset:16384
	ds_read_b128 v[236:239], v87 offset:18432
	ds_read_b128 v[240:243], v87 offset:20480
	ds_read_b128 v[244:247], v87 offset:22528
	ds_read_b128 v[100:103], v87 offset:32768
	ds_read_b128 v[104:107], v87 offset:34816
	ds_read_b128 v[68:71], v87 offset:36864
	ds_read_b128 v[80:83], v87 offset:38912
	ds_read_b128 v[216:219], v88
	ds_read_b128 v[220:223], v88 offset:2048
	ds_read_b128 v[224:227], v88 offset:4096
	ds_read_b128 v[228:231], v88 offset:6144
	ds_read_b128 v[248:251], v89 offset:16384
	ds_read_b128 v[252:255], v89 offset:18432
	ds_read_b128 v[92:95], v89 offset:20480
	ds_read_b128 v[96:99], v89 offset:22528
	ds_read_b128 v[200:203], v89 offset:32768
	ds_read_b128 v[164:167], v89 offset:34816
	ds_read_b128 v[112:115], v89 offset:36864
	ds_read_b128 v[76:79], v89 offset:38912
	s_waitcnt lgkmcnt(0)
	s_barrier
	s_cmp_eq_u32 s94, 15
	s_cbranch_scc1 .Lgp9_last
	s_add_u32 m0, s96, 0x0
	v_mfma_f32_16x16x32_bf16 v[60:63], v[232:235], v[192:195], v[60:63]
	global_load_lds_dwordx4 v72, s[90:91]
	v_mfma_f32_16x16x32_bf16 v[116:119], v[100:103], v[192:195], v[116:119]
	s_add_u32 m0, s96, 0x1000
	v_mfma_f32_16x16x32_bf16 v[56:59], v[236:239], v[192:195], v[56:59]
	global_load_lds_dwordx4 v73, s[90:91]
	v_mfma_f32_16x16x32_bf16 v[120:123], v[104:107], v[192:195], v[120:123]
	s_add_u32 m0, s96, 0x2000
	v_mfma_f32_16x16x32_bf16 v[52:55], v[240:243], v[192:195], v[52:55]
	global_load_lds_dwordx4 v66, s[90:91]
	v_mfma_f32_16x16x32_bf16 v[124:127], v[68:71], v[192:195], v[124:127]
	s_add_u32 m0, s96, 0x3000
	v_mfma_f32_16x16x32_bf16 v[48:51], v[244:247], v[192:195], v[48:51]
	global_load_lds_dwordx4 v67, s[90:91]
	v_mfma_f32_16x16x32_bf16 v[128:131], v[80:83], v[192:195], v[128:131]
	s_add_u32 m0, s96, 0x4000
	v_mfma_f32_16x16x32_bf16 v[44:47], v[232:235], v[204:207], v[44:47]
	global_load_lds_dwordx4 v72, s[92:93]
	v_mfma_f32_16x16x32_bf16 v[132:135], v[100:103], v[204:207], v[132:135]
	s_add_u32 m0, s96, 0x5000
	v_mfma_f32_16x16x32_bf16 v[40:43], v[236:239], v[204:207], v[40:43]
	global_load_lds_dwordx4 v73, s[92:93]
	v_mfma_f32_16x16x32_bf16 v[136:139], v[104:107], v[204:207], v[136:139]
	s_add_u32 m0, s96, 0x6000
	v_mfma_f32_16x16x32_bf16 v[36:39], v[240:243], v[204:207], v[36:39]
	global_load_lds_dwordx4 v66, s[92:93]
	v_mfma_f32_16x16x32_bf16 v[140:143], v[68:71], v[204:207], v[140:143]
	s_add_u32 m0, s96, 0x7000
	v_mfma_f32_16x16x32_bf16 v[32:35], v[244:247], v[204:207], v[32:35]
	global_load_lds_dwordx4 v67, s[92:93]
	v_mfma_f32_16x16x32_bf16 v[148:151], v[80:83], v[204:207], v[148:151]
	s_add_u32 m0, s96, 0x8000
	v_mfma_f32_16x16x32_bf16 v[28:31], v[232:235], v[208:211], v[28:31]
	global_load_lds_dwordx4 v72, s[98:99]
	v_mfma_f32_16x16x32_bf16 v[152:155], v[100:103], v[208:211], v[152:155]
	s_add_u32 m0, s96, 0x9000
	v_mfma_f32_16x16x32_bf16 v[24:27], v[236:239], v[208:211], v[24:27]
	global_load_lds_dwordx4 v73, s[98:99]
	v_mfma_f32_16x16x32_bf16 v[156:159], v[104:107], v[208:211], v[156:159]
	s_add_u32 m0, s96, 0xa000
	v_mfma_f32_16x16x32_bf16 v[20:23], v[240:243], v[208:211], v[20:23]
	global_load_lds_dwordx4 v66, s[98:99]
	v_mfma_f32_16x16x32_bf16 v[160:163], v[68:71], v[208:211], v[160:163]
	s_add_u32 m0, s96, 0xb000
	v_mfma_f32_16x16x32_bf16 v[16:19], v[244:247], v[208:211], v[16:19]
	global_load_lds_dwordx4 v67, s[98:99]
	s_add_u32 s90, s90, 0x80
	s_addc_u32 s91, s91, 0
	s_add_u32 s92, s92, 0x80
	s_addc_u32 s93, s93, 0
	s_add_u32 s98, s98, 0x80
	s_addc_u32 s99, s99, 0
	v_mfma_f32_16x16x32_bf16 v[172:175], v[80:83], v[208:211], v[172:175]
	v_mfma_f32_16x16x32_bf16 v[12:15], v[232:235], v[212:215], v[12:15]
	v_mfma_f32_16x16x32_bf16 v[176:179], v[100:103], v[212:215], v[176:179]
	v_mfma_f32_16x16x32_bf16 v[4:7], v[236:239], v[212:215], v[4:7]
	v_mfma_f32_16x16x32_bf16 v[180:183], v[104:107], v[212:215], v[180:183]
	v_mfma_f32_16x16x32_bf16 v[0:3], v[240:243], v[212:215], v[0:3]
	v_mfma_f32_16x16x32_bf16 v[184:187], v[68:71], v[212:215], v[184:187]
	v_mfma_f32_16x16x32_bf16 v[8:11], v[244:247], v[212:215], v[8:11]
	v_mfma_f32_16x16x32_bf16 v[188:191], v[80:83], v[212:215], v[188:191]
	v_mfma_f32_16x16x32_bf16 v[60:63], v[248:251], v[216:219], v[60:63]
	v_mfma_f32_16x16x32_bf16 v[116:119], v[200:203], v[216:219], v[116:119]
	v_mfma_f32_16x16x32_bf16 v[56:59], v[252:255], v[216:219], v[56:59]
	v_mfma_f32_16x16x32_bf16 v[120:123], v[164:167], v[216:219], v[120:123]
	v_mfma_f32_16x16x32_bf16 v[52:55], v[92:95], v[216:219], v[52:55]
	v_mfma_f32_16x16x32_bf16 v[124:127], v[112:115], v[216:219], v[124:127]
	v_mfma_f32_16x16x32_bf16 v[48:51], v[96:99], v[216:219], v[48:51]
	v_mfma_f32_16x16x32_bf16 v[128:131], v[76:79], v[216:219], v[128:131]
	v_mfma_f32_16x16x32_bf16 v[44:47], v[248:251], v[220:223], v[44:47]
	v_mfma_f32_16x16x32_bf16 v[132:135], v[200:203], v[220:223], v[132:135]
	v_mfma_f32_16x16x32_bf16 v[40:43], v[252:255], v[220:223], v[40:43]
	v_mfma_f32_16x16x32_bf16 v[136:139], v[164:167], v[220:223], v[136:139]
	v_mfma_f32_16x16x32_bf16 v[36:39], v[92:95], v[220:223], v[36:39]
	v_mfma_f32_16x16x32_bf16 v[140:143], v[112:115], v[220:223], v[140:143]
	v_mfma_f32_16x16x32_bf16 v[32:35], v[96:99], v[220:223], v[32:35]
	v_mfma_f32_16x16x32_bf16 v[148:151], v[76:79], v[220:223], v[148:151]
	v_mfma_f32_16x16x32_bf16 v[28:31], v[248:251], v[224:227], v[28:31]
	v_mfma_f32_16x16x32_bf16 v[152:155], v[200:203], v[224:227], v[152:155]
	v_mfma_f32_16x16x32_bf16 v[24:27], v[252:255], v[224:227], v[24:27]
	v_mfma_f32_16x16x32_bf16 v[156:159], v[164:167], v[224:227], v[156:159]
	v_mfma_f32_16x16x32_bf16 v[20:23], v[92:95], v[224:227], v[20:23]
	v_mfma_f32_16x16x32_bf16 v[160:163], v[112:115], v[224:227], v[160:163]
	v_mfma_f32_16x16x32_bf16 v[16:19], v[96:99], v[224:227], v[16:19]
	v_mfma_f32_16x16x32_bf16 v[172:175], v[76:79], v[224:227], v[172:175]
	v_mfma_f32_16x16x32_bf16 v[12:15], v[248:251], v[228:231], v[12:15]
	v_mfma_f32_16x16x32_bf16 v[176:179], v[200:203], v[228:231], v[176:179]
	v_mfma_f32_16x16x32_bf16 v[4:7], v[252:255], v[228:231], v[4:7]
	v_mfma_f32_16x16x32_bf16 v[180:183], v[164:167], v[228:231], v[180:183]
	v_mfma_f32_16x16x32_bf16 v[0:3], v[92:95], v[228:231], v[0:3]
	v_mfma_f32_16x16x32_bf16 v[184:187], v[112:115], v[228:231], v[184:187]
	v_mfma_f32_16x16x32_bf16 v[8:11], v[96:99], v[228:231], v[8:11]
	v_mfma_f32_16x16x32_bf16 v[188:191], v[76:79], v[228:231], v[188:191]
	s_add_u32 s94, s94, 1
	s_branch .Lgp9_loop
.Lgp9_last:
	v_mfma_f32_16x16x32_bf16 v[60:63], v[232:235], v[192:195], v[60:63]
	v_mfma_f32_16x16x32_bf16 v[116:119], v[100:103], v[192:195], v[116:119]
	v_mfma_f32_16x16x32_bf16 v[56:59], v[236:239], v[192:195], v[56:59]
	v_mfma_f32_16x16x32_bf16 v[120:123], v[104:107], v[192:195], v[120:123]
	v_mfma_f32_16x16x32_bf16 v[52:55], v[240:243], v[192:195], v[52:55]
	v_mfma_f32_16x16x32_bf16 v[124:127], v[68:71], v[192:195], v[124:127]
	v_mfma_f32_16x16x32_bf16 v[48:51], v[244:247], v[192:195], v[48:51]
	v_mfma_f32_16x16x32_bf16 v[128:131], v[80:83], v[192:195], v[128:131]
	v_mfma_f32_16x16x32_bf16 v[44:47], v[232:235], v[204:207], v[44:47]
	v_mfma_f32_16x16x32_bf16 v[132:135], v[100:103], v[204:207], v[132:135]
	v_mfma_f32_16x16x32_bf16 v[40:43], v[236:239], v[204:207], v[40:43]
	v_mfma_f32_16x16x32_bf16 v[136:139], v[104:107], v[204:207], v[136:139]
	v_mfma_f32_16x16x32_bf16 v[36:39], v[240:243], v[204:207], v[36:39]
	v_mfma_f32_16x16x32_bf16 v[140:143], v[68:71], v[204:207], v[140:143]
	v_mfma_f32_16x16x32_bf16 v[32:35], v[244:247], v[204:207], v[32:35]
	v_mfma_f32_16x16x32_bf16 v[148:151], v[80:83], v[204:207], v[148:151]
	v_mfma_f32_16x16x32_bf16 v[28:31], v[232:235], v[208:211], v[28:31]
	v_mfma_f32_16x16x32_bf16 v[152:155], v[100:103], v[208:211], v[152:155]
	v_mfma_f32_16x16x32_bf16 v[24:27], v[236:239], v[208:211], v[24:27]
	v_mfma_f32_16x16x32_bf16 v[156:159], v[104:107], v[208:211], v[156:159]
	v_mfma_f32_16x16x32_bf16 v[20:23], v[240:243], v[208:211], v[20:23]
	v_mfma_f32_16x16x32_bf16 v[160:163], v[68:71], v[208:211], v[160:163]
	v_mfma_f32_16x16x32_bf16 v[16:19], v[244:247], v[208:211], v[16:19]
	v_mfma_f32_16x16x32_bf16 v[172:175], v[80:83], v[208:211], v[172:175]
	v_mfma_f32_16x16x32_bf16 v[12:15], v[232:235], v[212:215], v[12:15]
	v_mfma_f32_16x16x32_bf16 v[176:179], v[100:103], v[212:215], v[176:179]
	v_mfma_f32_16x16x32_bf16 v[4:7], v[236:239], v[212:215], v[4:7]
	v_mfma_f32_16x16x32_bf16 v[180:183], v[104:107], v[212:215], v[180:183]
	v_mfma_f32_16x16x32_bf16 v[0:3], v[240:243], v[212:215], v[0:3]
	v_mfma_f32_16x16x32_bf16 v[184:187], v[68:71], v[212:215], v[184:187]
	v_mfma_f32_16x16x32_bf16 v[8:11], v[244:247], v[212:215], v[8:11]
	v_mfma_f32_16x16x32_bf16 v[188:191], v[80:83], v[212:215], v[188:191]
	v_mfma_f32_16x16x32_bf16 v[60:63], v[248:251], v[216:219], v[60:63]
	v_mfma_f32_16x16x32_bf16 v[116:119], v[200:203], v[216:219], v[116:119]
	v_mfma_f32_16x16x32_bf16 v[56:59], v[252:255], v[216:219], v[56:59]
	v_mfma_f32_16x16x32_bf16 v[120:123], v[164:167], v[216:219], v[120:123]
	v_mfma_f32_16x16x32_bf16 v[52:55], v[92:95], v[216:219], v[52:55]
	v_mfma_f32_16x16x32_bf16 v[124:127], v[112:115], v[216:219], v[124:127]
	v_mfma_f32_16x16x32_bf16 v[48:51], v[96:99], v[216:219], v[48:51]
	v_mfma_f32_16x16x32_bf16 v[128:131], v[76:79], v[216:219], v[128:131]
	v_mfma_f32_16x16x32_bf16 v[44:47], v[248:251], v[220:223], v[44:47]
	v_mfma_f32_16x16x32_bf16 v[132:135], v[200:203], v[220:223], v[132:135]
	v_mfma_f32_16x16x32_bf16 v[40:43], v[252:255], v[220:223], v[40:43]
	v_mfma_f32_16x16x32_bf16 v[136:139], v[164:167], v[220:223], v[136:139]
	v_mfma_f32_16x16x32_bf16 v[36:39], v[92:95], v[220:223], v[36:39]
	v_mfma_f32_16x16x32_bf16 v[140:143], v[112:115], v[220:223], v[140:143]
	v_mfma_f32_16x16x32_bf16 v[32:35], v[96:99], v[220:223], v[32:35]
	v_mfma_f32_16x16x32_bf16 v[148:151], v[76:79], v[220:223], v[148:151]
	v_mfma_f32_16x16x32_bf16 v[28:31], v[248:251], v[224:227], v[28:31]
	v_mfma_f32_16x16x32_bf16 v[152:155], v[200:203], v[224:227], v[152:155]
	v_mfma_f32_16x16x32_bf16 v[24:27], v[252:255], v[224:227], v[24:27]
	v_mfma_f32_16x16x32_bf16 v[156:159], v[164:167], v[224:227], v[156:159]
	v_mfma_f32_16x16x32_bf16 v[20:23], v[92:95], v[224:227], v[20:23]
	v_mfma_f32_16x16x32_bf16 v[160:163], v[112:115], v[224:227], v[160:163]
	v_mfma_f32_16x16x32_bf16 v[16:19], v[96:99], v[224:227], v[16:19]
	v_mfma_f32_16x16x32_bf16 v[172:175], v[76:79], v[224:227], v[172:175]
	v_mfma_f32_16x16x32_bf16 v[12:15], v[248:251], v[228:231], v[12:15]
	v_mfma_f32_16x16x32_bf16 v[176:179], v[200:203], v[228:231], v[176:179]
	v_mfma_f32_16x16x32_bf16 v[4:7], v[252:255], v[228:231], v[4:7]
	v_mfma_f32_16x16x32_bf16 v[180:183], v[164:167], v[228:231], v[180:183]
	v_mfma_f32_16x16x32_bf16 v[0:3], v[92:95], v[228:231], v[0:3]
	v_mfma_f32_16x16x32_bf16 v[184:187], v[112:115], v[228:231], v[184:187]
	v_mfma_f32_16x16x32_bf16 v[8:11], v[96:99], v[228:231], v[8:11]
	v_mfma_f32_16x16x32_bf16 v[188:191], v[76:79], v[228:231], v[188:191]
	s_nop 7
	s_nop 3
	s_lshl_b32 s95, s95, 1
	s_branch .Lgp9_done
.Lgp9_unpark:
	v_mov_b32_e32 v60, v116
	v_mov_b32_e32 v61, v117
	v_mov_b32_e32 v62, v118
	v_mov_b32_e32 v63, v119
	v_mov_b32_e32 v56, v120
	v_mov_b32_e32 v57, v121
	v_mov_b32_e32 v58, v122
	v_mov_b32_e32 v59, v123
	v_mov_b32_e32 v52, v124
	v_mov_b32_e32 v53, v125
	v_mov_b32_e32 v54, v126
	v_mov_b32_e32 v55, v127
	v_mov_b32_e32 v48, v128
	v_mov_b32_e32 v49, v129
	v_mov_b32_e32 v50, v130
	v_mov_b32_e32 v51, v131
	v_mov_b32_e32 v44, v132
	v_mov_b32_e32 v45, v133
	v_mov_b32_e32 v46, v134
	v_mov_b32_e32 v47, v135
	v_mov_b32_e32 v40, v136
	v_mov_b32_e32 v41, v137
	v_mov_b32_e32 v42, v138
	v_mov_b32_e32 v43, v139
	v_mov_b32_e32 v36, v140
	v_mov_b32_e32 v37, v141
	v_mov_b32_e32 v38, v142
	v_mov_b32_e32 v39, v143
	v_mov_b32_e32 v32, v148
	v_mov_b32_e32 v33, v149
	v_mov_b32_e32 v34, v150
	v_mov_b32_e32 v35, v151
	v_mov_b32_e32 v28, v152
	v_mov_b32_e32 v29, v153
	v_mov_b32_e32 v30, v154
	v_mov_b32_e32 v31, v155
	v_mov_b32_e32 v24, v156
	v_mov_b32_e32 v25, v157
	v_mov_b32_e32 v26, v158
	v_mov_b32_e32 v27, v159
	v_mov_b32_e32 v20, v160
	v_mov_b32_e32 v21, v161
	v_mov_b32_e32 v22, v162
	v_mov_b32_e32 v23, v163
	v_mov_b32_e32 v16, v172
	v_mov_b32_e32 v17, v173
	v_mov_b32_e32 v18, v174
	v_mov_b32_e32 v19, v175
	v_mov_b32_e32 v12, v176
	v_mov_b32_e32 v13, v177
	v_mov_b32_e32 v14, v178
	v_mov_b32_e32 v15, v179
	v_mov_b32_e32 v4, v180
	v_mov_b32_e32 v5, v181
	v_mov_b32_e32 v6, v182
	v_mov_b32_e32 v7, v183
	v_mov_b32_e32 v0, v184
	v_mov_b32_e32 v1, v185
	v_mov_b32_e32 v2, v186
	v_mov_b32_e32 v3, v187
	v_mov_b32_e32 v8, v188
	v_mov_b32_e32 v9, v189
	v_mov_b32_e32 v10, v190
	v_mov_b32_e32 v11, v191
	s_mov_b32 s95, 0
.Lgp9_done:
	v_lshl_add_u32 v166, s50, 7, v90
	v_lshl_or_b32 v198, s48, 7, v91
	v_ashrrev_i32_e32 v199, 31, v198
	v_ashrrev_i32_e32 v167, 31, v166
	v_lshl_add_u64 v[198:199], v[198:199], 1, s[14:15]
	v_lshlrev_b64 v[200:201], 12, v[166:167]
	v_lshl_add_u64 v[200:201], v[198:199], 0, v[200:201]
	s_lshl_b32 s44, s50, 6
	s_lshl_b32 s49, s48, 2
	s_add_i32 s49, s49, s44
	s_lshl_b32 s44, s50, 18
	s_lshl_b32 s48, s48, 14
	s_add_i32 s48, s44, s48
	s_mov_b32 s50, 0
	s_waitcnt lgkmcnt(0)
	s_waitcnt lgkmcnt(0)
	s_waitcnt vmcnt(0) lgkmcnt(0)
	s_waitcnt lgkmcnt(0)
	s_waitcnt lgkmcnt(0)
	s_nop 5
	v_and_b32_sdwa v111, v62, v108 dst_sel:DWORD dst_unused:UNUSED_PAD src0_sel:WORD_1 src1_sel:DWORD
	v_add3_u32 v62, v62, v111, s66
	v_and_b32_sdwa v111, v63, v108 dst_sel:DWORD dst_unused:UNUSED_PAD src0_sel:WORD_1 src1_sel:DWORD
	v_and_b32_sdwa v145, v60, v108 dst_sel:DWORD dst_unused:UNUSED_PAD src0_sel:WORD_1 src1_sel:DWORD
	v_add3_u32 v63, v63, v111, s66
	v_add3_u32 v60, v60, v145, s66
	v_and_b32_e32 v63, 0xffff0000, v63
	v_and_b32_sdwa v112, v61, v108 dst_sel:DWORD dst_unused:UNUSED_PAD src0_sel:WORD_1 src1_sel:DWORD
	v_add3_u32 v61, v61, v112, s66
	v_and_b32_e32 v78, 0xffff0000, v61
	v_or_b32_sdwa v61, v63, v62 dst_sel:DWORD dst_unused:UNUSED_PAD src0_sel:DWORD src1_sel:WORD_1
	v_or_b32_sdwa v60, v78, v60 dst_sel:DWORD dst_unused:UNUSED_PAD src0_sel:DWORD src1_sel:WORD_1
	global_store_dwordx2 v[200:201], v[60:61], off
	s_nop 1
	v_and_b32_sdwa v60, v58, v108 dst_sel:DWORD dst_unused:UNUSED_PAD src0_sel:WORD_1 src1_sel:DWORD
	v_and_b32_sdwa v61, v56, v108 dst_sel:DWORD dst_unused:UNUSED_PAD src0_sel:WORD_1 src1_sel:DWORD
	v_add3_u32 v56, v56, v61, s66
	v_add3_u32 v58, v58, v60, s66
	v_and_b32_sdwa v60, v59, v108 dst_sel:DWORD dst_unused:UNUSED_PAD src0_sel:WORD_1 src1_sel:DWORD
	v_and_b32_sdwa v61, v57, v108 dst_sel:DWORD dst_unused:UNUSED_PAD src0_sel:WORD_1 src1_sel:DWORD
	v_add3_u32 v59, v59, v60, s66
	v_add3_u32 v57, v57, v61, s66
	v_and_b32_e32 v59, 0xffff0000, v59
	v_and_b32_e32 v60, 0xffff0000, v57
	v_or_b32_sdwa v57, v59, v58 dst_sel:DWORD dst_unused:UNUSED_PAD src0_sel:DWORD src1_sel:WORD_1
	v_or_b32_sdwa v56, v60, v56 dst_sel:DWORD dst_unused:UNUSED_PAD src0_sel:DWORD src1_sel:WORD_1
	global_store_dwordx2 v[200:201], v[56:57], off offset:32
	v_and_b32_sdwa v56, v54, v108 dst_sel:DWORD dst_unused:UNUSED_PAD src0_sel:WORD_1 src1_sel:DWORD
	v_and_b32_sdwa v57, v52, v108 dst_sel:DWORD dst_unused:UNUSED_PAD src0_sel:WORD_1 src1_sel:DWORD
	v_add3_u32 v52, v52, v57, s66
	v_add3_u32 v54, v54, v56, s66
	v_and_b32_sdwa v56, v55, v108 dst_sel:DWORD dst_unused:UNUSED_PAD src0_sel:WORD_1 src1_sel:DWORD
	v_and_b32_sdwa v57, v53, v108 dst_sel:DWORD dst_unused:UNUSED_PAD src0_sel:WORD_1 src1_sel:DWORD
	v_add3_u32 v55, v55, v56, s66
	v_add3_u32 v53, v53, v57, s66
	v_and_b32_e32 v55, 0xffff0000, v55
	v_and_b32_e32 v56, 0xffff0000, v53
	v_or_b32_sdwa v53, v55, v54 dst_sel:DWORD dst_unused:UNUSED_PAD src0_sel:DWORD src1_sel:WORD_1
	v_or_b32_sdwa v52, v56, v52 dst_sel:DWORD dst_unused:UNUSED_PAD src0_sel:DWORD src1_sel:WORD_1
	global_store_dwordx2 v[200:201], v[52:53], off offset:64
	s_nop 2
	v_and_b32_sdwa v52, v50, v108 dst_sel:DWORD dst_unused:UNUSED_PAD src0_sel:WORD_1 src1_sel:DWORD
	v_and_b32_sdwa v53, v48, v108 dst_sel:DWORD dst_unused:UNUSED_PAD src0_sel:WORD_1 src1_sel:DWORD
	v_add3_u32 v48, v48, v53, s66
	v_add3_u32 v50, v50, v52, s66
	v_and_b32_sdwa v52, v51, v108 dst_sel:DWORD dst_unused:UNUSED_PAD src0_sel:WORD_1 src1_sel:DWORD
	v_and_b32_sdwa v53, v49, v108 dst_sel:DWORD dst_unused:UNUSED_PAD src0_sel:WORD_1 src1_sel:DWORD
	v_add3_u32 v51, v51, v52, s66
	v_add3_u32 v49, v49, v53, s66
	v_and_b32_e32 v51, 0xffff0000, v51
	v_and_b32_e32 v52, 0xffff0000, v49
	v_or_b32_sdwa v49, v51, v50 dst_sel:DWORD dst_unused:UNUSED_PAD src0_sel:DWORD src1_sel:WORD_1
	v_or_b32_sdwa v48, v52, v48 dst_sel:DWORD dst_unused:UNUSED_PAD src0_sel:DWORD src1_sel:WORD_1
	v_and_b32_sdwa v50, v46, v108 dst_sel:DWORD dst_unused:UNUSED_PAD src0_sel:WORD_1 src1_sel:DWORD
	v_and_b32_sdwa v51, v44, v108 dst_sel:DWORD dst_unused:UNUSED_PAD src0_sel:WORD_1 src1_sel:DWORD
	global_store_dwordx2 v[200:201], v[48:49], off offset:96
	v_or_b32_e32 v48, 16, v166
	v_add3_u32 v44, v44, v51, s66
	v_add3_u32 v46, v46, v50, s66
	v_and_b32_sdwa v50, v47, v108 dst_sel:DWORD dst_unused:UNUSED_PAD src0_sel:WORD_1 src1_sel:DWORD
	v_and_b32_sdwa v51, v45, v108 dst_sel:DWORD dst_unused:UNUSED_PAD src0_sel:WORD_1 src1_sel:DWORD
	v_ashrrev_i32_e32 v49, 31, v48
	v_add3_u32 v47, v47, v50, s66
	v_add3_u32 v45, v45, v51, s66
	v_lshlrev_b64 v[48:49], 12, v[48:49]
	v_and_b32_e32 v47, 0xffff0000, v47
	v_and_b32_e32 v50, 0xffff0000, v45
	v_lshl_add_u64 v[48:49], v[198:199], 0, v[48:49]
	v_or_b32_sdwa v45, v47, v46 dst_sel:DWORD dst_unused:UNUSED_PAD src0_sel:DWORD src1_sel:WORD_1
	v_or_b32_sdwa v44, v50, v44 dst_sel:DWORD dst_unused:UNUSED_PAD src0_sel:DWORD src1_sel:WORD_1
	global_store_dwordx2 v[48:49], v[44:45], off
	v_and_b32_sdwa v44, v42, v108 dst_sel:DWORD dst_unused:UNUSED_PAD src0_sel:WORD_1 src1_sel:DWORD
	v_and_b32_sdwa v45, v40, v108 dst_sel:DWORD dst_unused:UNUSED_PAD src0_sel:WORD_1 src1_sel:DWORD
	v_add3_u32 v40, v40, v45, s66
	v_add3_u32 v42, v42, v44, s66
	v_and_b32_sdwa v44, v43, v108 dst_sel:DWORD dst_unused:UNUSED_PAD src0_sel:WORD_1 src1_sel:DWORD
	v_and_b32_sdwa v45, v41, v108 dst_sel:DWORD dst_unused:UNUSED_PAD src0_sel:WORD_1 src1_sel:DWORD
	v_add3_u32 v43, v43, v44, s66
	v_add3_u32 v41, v41, v45, s66
	v_and_b32_e32 v43, 0xffff0000, v43
	v_and_b32_e32 v44, 0xffff0000, v41
	v_or_b32_sdwa v41, v43, v42 dst_sel:DWORD dst_unused:UNUSED_PAD src0_sel:DWORD src1_sel:WORD_1
	v_or_b32_sdwa v40, v44, v40 dst_sel:DWORD dst_unused:UNUSED_PAD src0_sel:DWORD src1_sel:WORD_1
	global_store_dwordx2 v[48:49], v[40:41], off offset:32
	v_and_b32_sdwa v40, v38, v108 dst_sel:DWORD dst_unused:UNUSED_PAD src0_sel:WORD_1 src1_sel:DWORD
	v_and_b32_sdwa v41, v36, v108 dst_sel:DWORD dst_unused:UNUSED_PAD src0_sel:WORD_1 src1_sel:DWORD
	v_add3_u32 v36, v36, v41, s66
	v_add3_u32 v38, v38, v40, s66
	v_and_b32_sdwa v40, v39, v108 dst_sel:DWORD dst_unused:UNUSED_PAD src0_sel:WORD_1 src1_sel:DWORD
	v_and_b32_sdwa v41, v37, v108 dst_sel:DWORD dst_unused:UNUSED_PAD src0_sel:WORD_1 src1_sel:DWORD
	v_add3_u32 v39, v39, v40, s66
	v_add3_u32 v37, v37, v41, s66
	v_and_b32_e32 v39, 0xffff0000, v39
	v_and_b32_e32 v40, 0xffff0000, v37
	v_or_b32_sdwa v37, v39, v38 dst_sel:DWORD dst_unused:UNUSED_PAD src0_sel:DWORD src1_sel:WORD_1
	v_or_b32_sdwa v36, v40, v36 dst_sel:DWORD dst_unused:UNUSED_PAD src0_sel:DWORD src1_sel:WORD_1
	global_store_dwordx2 v[48:49], v[36:37], off offset:64
	v_and_b32_sdwa v36, v34, v108 dst_sel:DWORD dst_unused:UNUSED_PAD src0_sel:WORD_1 src1_sel:DWORD
	v_and_b32_sdwa v37, v32, v108 dst_sel:DWORD dst_unused:UNUSED_PAD src0_sel:WORD_1 src1_sel:DWORD
	v_add3_u32 v32, v32, v37, s66
	v_add3_u32 v34, v34, v36, s66
	v_and_b32_sdwa v36, v35, v108 dst_sel:DWORD dst_unused:UNUSED_PAD src0_sel:WORD_1 src1_sel:DWORD
	v_and_b32_sdwa v37, v33, v108 dst_sel:DWORD dst_unused:UNUSED_PAD src0_sel:WORD_1 src1_sel:DWORD
	v_add3_u32 v35, v35, v36, s66
	v_add3_u32 v33, v33, v37, s66
	v_and_b32_e32 v35, 0xffff0000, v35
	v_and_b32_e32 v36, 0xffff0000, v33
	v_or_b32_sdwa v33, v35, v34 dst_sel:DWORD dst_unused:UNUSED_PAD src0_sel:DWORD src1_sel:WORD_1
	v_or_b32_sdwa v32, v36, v32 dst_sel:DWORD dst_unused:UNUSED_PAD src0_sel:DWORD src1_sel:WORD_1
	v_and_b32_sdwa v34, v30, v108 dst_sel:DWORD dst_unused:UNUSED_PAD src0_sel:WORD_1 src1_sel:DWORD
	v_and_b32_sdwa v35, v28, v108 dst_sel:DWORD dst_unused:UNUSED_PAD src0_sel:WORD_1 src1_sel:DWORD
	global_store_dwordx2 v[48:49], v[32:33], off offset:96
	v_or_b32_e32 v32, 32, v166
	v_add3_u32 v28, v28, v35, s66
	v_add3_u32 v30, v30, v34, s66
	v_and_b32_sdwa v34, v31, v108 dst_sel:DWORD dst_unused:UNUSED_PAD src0_sel:WORD_1 src1_sel:DWORD
	v_and_b32_sdwa v35, v29, v108 dst_sel:DWORD dst_unused:UNUSED_PAD src0_sel:WORD_1 src1_sel:DWORD
	v_ashrrev_i32_e32 v33, 31, v32
	v_add3_u32 v31, v31, v34, s66
	v_add3_u32 v29, v29, v35, s66
	v_lshlrev_b64 v[32:33], 12, v[32:33]
	v_and_b32_e32 v31, 0xffff0000, v31
	v_and_b32_e32 v34, 0xffff0000, v29
	v_lshl_add_u64 v[32:33], v[198:199], 0, v[32:33]
	v_or_b32_sdwa v29, v31, v30 dst_sel:DWORD dst_unused:UNUSED_PAD src0_sel:DWORD src1_sel:WORD_1
	v_or_b32_sdwa v28, v34, v28 dst_sel:DWORD dst_unused:UNUSED_PAD src0_sel:DWORD src1_sel:WORD_1
	global_store_dwordx2 v[32:33], v[28:29], off
	v_and_b32_sdwa v28, v26, v108 dst_sel:DWORD dst_unused:UNUSED_PAD src0_sel:WORD_1 src1_sel:DWORD
	v_and_b32_sdwa v29, v24, v108 dst_sel:DWORD dst_unused:UNUSED_PAD src0_sel:WORD_1 src1_sel:DWORD
	v_add3_u32 v24, v24, v29, s66
	v_add3_u32 v26, v26, v28, s66
	v_and_b32_sdwa v28, v27, v108 dst_sel:DWORD dst_unused:UNUSED_PAD src0_sel:WORD_1 src1_sel:DWORD
	v_and_b32_sdwa v29, v25, v108 dst_sel:DWORD dst_unused:UNUSED_PAD src0_sel:WORD_1 src1_sel:DWORD
	v_add3_u32 v27, v27, v28, s66
	v_add3_u32 v25, v25, v29, s66
	v_and_b32_e32 v27, 0xffff0000, v27
	v_and_b32_e32 v28, 0xffff0000, v25
	v_or_b32_sdwa v25, v27, v26 dst_sel:DWORD dst_unused:UNUSED_PAD src0_sel:DWORD src1_sel:WORD_1
	v_or_b32_sdwa v24, v28, v24 dst_sel:DWORD dst_unused:UNUSED_PAD src0_sel:DWORD src1_sel:WORD_1
	global_store_dwordx2 v[32:33], v[24:25], off offset:32
	v_and_b32_sdwa v24, v22, v108 dst_sel:DWORD dst_unused:UNUSED_PAD src0_sel:WORD_1 src1_sel:DWORD
	v_and_b32_sdwa v25, v20, v108 dst_sel:DWORD dst_unused:UNUSED_PAD src0_sel:WORD_1 src1_sel:DWORD
	v_add3_u32 v20, v20, v25, s66
	v_add3_u32 v22, v22, v24, s66
	v_and_b32_sdwa v24, v23, v108 dst_sel:DWORD dst_unused:UNUSED_PAD src0_sel:WORD_1 src1_sel:DWORD
	v_and_b32_sdwa v25, v21, v108 dst_sel:DWORD dst_unused:UNUSED_PAD src0_sel:WORD_1 src1_sel:DWORD
	v_add3_u32 v23, v23, v24, s66
	v_add3_u32 v21, v21, v25, s66
	v_and_b32_e32 v23, 0xffff0000, v23
	v_and_b32_e32 v24, 0xffff0000, v21
	v_or_b32_sdwa v21, v23, v22 dst_sel:DWORD dst_unused:UNUSED_PAD src0_sel:DWORD src1_sel:WORD_1
	v_or_b32_sdwa v20, v24, v20 dst_sel:DWORD dst_unused:UNUSED_PAD src0_sel:DWORD src1_sel:WORD_1
	global_store_dwordx2 v[32:33], v[20:21], off offset:64
	v_and_b32_sdwa v20, v18, v108 dst_sel:DWORD dst_unused:UNUSED_PAD src0_sel:WORD_1 src1_sel:DWORD
	v_and_b32_sdwa v21, v16, v108 dst_sel:DWORD dst_unused:UNUSED_PAD src0_sel:WORD_1 src1_sel:DWORD
	v_add3_u32 v16, v16, v21, s66
	v_add3_u32 v18, v18, v20, s66
	v_and_b32_sdwa v20, v19, v108 dst_sel:DWORD dst_unused:UNUSED_PAD src0_sel:WORD_1 src1_sel:DWORD
	v_and_b32_sdwa v21, v17, v108 dst_sel:DWORD dst_unused:UNUSED_PAD src0_sel:WORD_1 src1_sel:DWORD
	v_add3_u32 v19, v19, v20, s66
	v_add3_u32 v17, v17, v21, s66
	v_and_b32_e32 v19, 0xffff0000, v19
	v_and_b32_e32 v20, 0xffff0000, v17
	v_or_b32_sdwa v17, v19, v18 dst_sel:DWORD dst_unused:UNUSED_PAD src0_sel:DWORD src1_sel:WORD_1
	v_or_b32_sdwa v16, v20, v16 dst_sel:DWORD dst_unused:UNUSED_PAD src0_sel:DWORD src1_sel:WORD_1
	v_and_b32_sdwa v18, v14, v108 dst_sel:DWORD dst_unused:UNUSED_PAD src0_sel:WORD_1 src1_sel:DWORD
	v_and_b32_sdwa v19, v12, v108 dst_sel:DWORD dst_unused:UNUSED_PAD src0_sel:WORD_1 src1_sel:DWORD
	global_store_dwordx2 v[32:33], v[16:17], off offset:96
	v_or_b32_e32 v16, 48, v166
	v_add3_u32 v12, v12, v19, s66
	v_add3_u32 v14, v14, v18, s66
	v_and_b32_sdwa v18, v15, v108 dst_sel:DWORD dst_unused:UNUSED_PAD src0_sel:WORD_1 src1_sel:DWORD
	v_and_b32_sdwa v19, v13, v108 dst_sel:DWORD dst_unused:UNUSED_PAD src0_sel:WORD_1 src1_sel:DWORD
	v_ashrrev_i32_e32 v17, 31, v16
	v_add3_u32 v15, v15, v18, s66
	v_add3_u32 v13, v13, v19, s66
	v_lshlrev_b64 v[16:17], 12, v[16:17]
	v_and_b32_e32 v15, 0xffff0000, v15
	v_and_b32_e32 v18, 0xffff0000, v13
	v_lshl_add_u64 v[16:17], v[198:199], 0, v[16:17]
	v_or_b32_sdwa v13, v15, v14 dst_sel:DWORD dst_unused:UNUSED_PAD src0_sel:DWORD src1_sel:WORD_1
	v_or_b32_sdwa v12, v18, v12 dst_sel:DWORD dst_unused:UNUSED_PAD src0_sel:DWORD src1_sel:WORD_1
	global_store_dwordx2 v[16:17], v[12:13], off
	v_and_b32_sdwa v12, v6, v108 dst_sel:DWORD dst_unused:UNUSED_PAD src0_sel:WORD_1 src1_sel:DWORD
	v_and_b32_sdwa v13, v4, v108 dst_sel:DWORD dst_unused:UNUSED_PAD src0_sel:WORD_1 src1_sel:DWORD
	v_add3_u32 v4, v4, v13, s66
	v_add3_u32 v6, v6, v12, s66
	v_and_b32_sdwa v12, v7, v108 dst_sel:DWORD dst_unused:UNUSED_PAD src0_sel:WORD_1 src1_sel:DWORD
	v_and_b32_sdwa v13, v5, v108 dst_sel:DWORD dst_unused:UNUSED_PAD src0_sel:WORD_1 src1_sel:DWORD
	v_add3_u32 v7, v7, v12, s66
	v_add3_u32 v5, v5, v13, s66
	v_and_b32_e32 v7, 0xffff0000, v7
	v_and_b32_e32 v12, 0xffff0000, v5
	v_or_b32_sdwa v5, v7, v6 dst_sel:DWORD dst_unused:UNUSED_PAD src0_sel:DWORD src1_sel:WORD_1
	v_or_b32_sdwa v4, v12, v4 dst_sel:DWORD dst_unused:UNUSED_PAD src0_sel:DWORD src1_sel:WORD_1
	global_store_dwordx2 v[16:17], v[4:5], off offset:32
	v_and_b32_sdwa v4, v2, v108 dst_sel:DWORD dst_unused:UNUSED_PAD src0_sel:WORD_1 src1_sel:DWORD
	v_and_b32_sdwa v5, v0, v108 dst_sel:DWORD dst_unused:UNUSED_PAD src0_sel:WORD_1 src1_sel:DWORD
	v_add3_u32 v0, v0, v5, s66
	v_add3_u32 v2, v2, v4, s66
	v_and_b32_sdwa v4, v3, v108 dst_sel:DWORD dst_unused:UNUSED_PAD src0_sel:WORD_1 src1_sel:DWORD
	v_and_b32_sdwa v5, v1, v108 dst_sel:DWORD dst_unused:UNUSED_PAD src0_sel:WORD_1 src1_sel:DWORD
	v_add3_u32 v3, v3, v4, s66
	v_add3_u32 v1, v1, v5, s66
	v_and_b32_e32 v3, 0xffff0000, v3
	v_and_b32_e32 v4, 0xffff0000, v1
	v_or_b32_sdwa v1, v3, v2 dst_sel:DWORD dst_unused:UNUSED_PAD src0_sel:DWORD src1_sel:WORD_1
	v_or_b32_sdwa v0, v4, v0 dst_sel:DWORD dst_unused:UNUSED_PAD src0_sel:DWORD src1_sel:WORD_1
	global_store_dwordx2 v[16:17], v[0:1], off offset:64
	v_and_b32_sdwa v1, v8, v108 dst_sel:DWORD dst_unused:UNUSED_PAD src0_sel:WORD_1 src1_sel:DWORD
	v_add3_u32 v2, v8, v1, s66
	v_and_b32_sdwa v1, v11, v108 dst_sel:DWORD dst_unused:UNUSED_PAD src0_sel:WORD_1 src1_sel:DWORD
	v_and_b32_sdwa v3, v9, v108 dst_sel:DWORD dst_unused:UNUSED_PAD src0_sel:WORD_1 src1_sel:DWORD
	v_and_b32_sdwa v0, v10, v108 dst_sel:DWORD dst_unused:UNUSED_PAD src0_sel:WORD_1 src1_sel:DWORD
	v_add3_u32 v1, v11, v1, s66
	v_add3_u32 v3, v9, v3, s66
	v_add3_u32 v0, v10, v0, s66
	v_and_b32_e32 v1, 0xffff0000, v1
	v_and_b32_e32 v3, 0xffff0000, v3
	v_or_b32_sdwa v1, v1, v0 dst_sel:DWORD dst_unused:UNUSED_PAD src0_sel:DWORD src1_sel:WORD_1
	v_or_b32_sdwa v0, v3, v2 dst_sel:DWORD dst_unused:UNUSED_PAD src0_sel:DWORD src1_sel:WORD_1
	global_store_dwordx2 v[16:17], v[0:1], off offset:96

	.amdhsa_kernel _Z8fwd_mega6Paramsii
		.amdhsa_group_segment_fixed_size 16
		.amdhsa_private_segment_fixed_size 0
		.amdhsa_kernarg_size 560
		.amdhsa_user_sgpr_count 2
		.amdhsa_user_sgpr_dispatch_ptr 0
		.amdhsa_user_sgpr_queue_ptr 0
		.amdhsa_user_sgpr_kernarg_segment_ptr 1
		.amdhsa_user_sgpr_dispatch_id 0
		.amdhsa_user_sgpr_kernarg_preload_length 0
		.amdhsa_user_sgpr_kernarg_preload_offset 0
		.amdhsa_user_sgpr_private_segment_size 0
		.amdhsa_uses_dynamic_stack 0
		.amdhsa_enable_private_segment 0
		.amdhsa_system_sgpr_workgroup_id_x 1
		.amdhsa_system_sgpr_workgroup_id_y 0
		.amdhsa_system_sgpr_workgroup_id_z 0
		.amdhsa_system_sgpr_workgroup_info 0
		.amdhsa_system_vgpr_workitem_id 2
		.amdhsa_next_free_vgpr 256
		.amdhsa_next_free_sgpr 102
		.amdhsa_accum_offset 256
		.amdhsa_reserve_vcc 1
		.amdhsa_float_round_mode_32 0
		.amdhsa_float_round_mode_16_64 0
		.amdhsa_float_denorm_mode_32 3
		.amdhsa_float_denorm_mode_16_64 3
		.amdhsa_dx10_clamp 1
		.amdhsa_ieee_mode 1
		.amdhsa_fp16_overflow 0
		.amdhsa_tg_split 0
		.amdhsa_exception_fp_ieee_invalid_op 0
		.amdhsa_exception_fp_denorm_src 0
		.amdhsa_exception_fp_ieee_div_zero 0
		.amdhsa_exception_fp_ieee_overflow 0
		.amdhsa_exception_fp_ieee_underflow 0
		.amdhsa_exception_fp_ieee_inexact 0
		.amdhsa_exception_int_div_zero 0
	.end_amdhsa_kernel

.Lfunc_end0:
	.size	_Z8fwd_mega6Paramsii, .Lfunc_end0-_Z8fwd_mega6Paramsii
	.set _Z8fwd_mega6Paramsii.num_vgpr, 256
	.set _Z8fwd_mega6Paramsii.num_agpr, 0
	.set _Z8fwd_mega6Paramsii.numbered_sgpr, 102
	.set _Z8fwd_mega6Paramsii.num_named_barrier, 0
	.set _Z8fwd_mega6Paramsii.private_seg_size, 0
	.set _Z8fwd_mega6Paramsii.uses_vcc, 1
	.set _Z8fwd_mega6Paramsii.uses_flat_scratch, 0
	.set _Z8fwd_mega6Paramsii.has_dyn_sized_stack, 0
	.set _Z8fwd_mega6Paramsii.has_recursion, 0
	.set _Z8fwd_mega6Paramsii.has_indirect_call, 0

amdhsa.kernels:
  - .agpr_count:     0
    .args:
      - .offset:         0
        .size:           296
        .value_kind:     by_value
      - .offset:         296
        .size:           4
        .value_kind:     by_value
      - .offset:         300
        .size:           4
        .value_kind:     by_value
      - .offset:         304
        .size:           4
        .value_kind:     hidden_block_count_x
      - .offset:         308
        .size:           4
        .value_kind:     hidden_block_count_y
      - .offset:         312
        .size:           4
        .value_kind:     hidden_block_count_z
      - .offset:         316
        .size:           2
        .value_kind:     hidden_group_size_x
      - .offset:         318
        .size:           2
        .value_kind:     hidden_group_size_y
      - .offset:         320
        .size:           2
        .value_kind:     hidden_group_size_z
      - .offset:         322
        .size:           2
        .value_kind:     hidden_remainder_x
      - .offset:         324
        .size:           2
        .value_kind:     hidden_remainder_y
      - .offset:         326
        .size:           2
        .value_kind:     hidden_remainder_z
      - .offset:         344
        .size:           8
        .value_kind:     hidden_global_offset_x
      - .offset:         352
        .size:           8
        .value_kind:     hidden_global_offset_y
      - .offset:         360
        .size:           8
        .value_kind:     hidden_global_offset_z
      - .offset:         368
        .size:           2
        .value_kind:     hidden_grid_dims
      - .offset:         392
        .size:           8
        .value_kind:     hidden_multigrid_sync_arg
      - .offset:         424
        .size:           4
        .value_kind:     hidden_dynamic_lds_size
    .group_segment_fixed_size: 16
    .kernarg_segment_align: 8
    .kernarg_segment_size: 560
    .language:       OpenCL C
    .language_version:
      - 2
      - 0
    .max_flat_workgroup_size: 256
    .name:           _Z8fwd_mega6Paramsii
    .private_segment_fixed_size: 0
    .sgpr_count:     108
    .sgpr_spill_count: 0
    .symbol:         _Z8fwd_mega6Paramsii.kd
    .uniform_work_group_size: 1
    .uses_dynamic_stack: false
    .vgpr_count:     256
    .vgpr_spill_count: 0
    .wavefront_size: 64
